# P6: end-of-GEMM drain after up and after gate waits only for the trailing LDS-DMA loads (vmcnt(16): the 16 epilogue stores stay in flight into the next GEMM's prologue)
# speedup vs baseline: 1.0108x; 1.0021x over previous
; #define PG8_WAIT_V(n) asm volatile("s_waitcnt vmcnt(" #n ")" ::: "memory")
; #define PG8_BAR __builtin_amdgcn_s_barrier()
; template <class Epi, class Sched, bool ALIGN_EPI = false, bool SP2 = false>
; __device__ __forceinline__ void gemm_phase(PG8_LAS unsigned char* lds, const Gemm g, const Sched& S, const Epi& E, const int wid_s) {
;     ...
;     PG8_WAIT_V(0);
;     if constexpr (!ALIGN_EPI) { if (wr == 0) PG8_BAR; }
;     PG8_BAR;
.LBB0_829:
	s_waitcnt vmcnt(16)
	s_barrier
